# stack_g with the snake reorder skipped for the one dependent MFMA pair in G2 (shifting accumulators)
# speedup vs baseline: 1.0007x; 1.0007x over previous
; #define PG8_STAGE(bufoff, gbase, voff) do { const int so_ = (int)(unsigned)((const char*)(gbase) - base_##voff); _Pragma("unroll") for (int _i = 0; _i < 2; ++_i) \
;         __builtin_amdgcn_raw_ptr_buffer_load_lds(rs_##voff, (PG8_LAS unsigned*)(lds + (bufoff) + ldsw + _i * 8192), 16, (int)(voff)[_i], so_, 0, 0); } while (0)
; #define PG8_LDA(dst, b, h) do { _Pragma("unroll") for (int m = 0; m < 4; ++m) _Pragma("unroll") for (int k = 0; k < 2; ++k) dst[m][k] = *(const PG8_LAS bf16x8*)(lds + PG8_SA(b, h) + aoff + m * 2048 + k * 1024); } while (0)
; #define PG8_LDB(dst, b, h) do { _Pragma("unroll") for (int n = 0; n < 2; ++n) _Pragma("unroll") for (int k = 0; k < 2; ++k) dst[n][k] = *(const PG8_LAS bf16x8*)(lds + PG8_SB(b, h) + boff + n * 2048 + k * 1024); } while (0)
; #define PG8_MMA(ai, bj, At, Bt) do { __builtin_amdgcn_s_setprio(1); _Pragma("unroll") for (int m = 0; m < 4; ++m) _Pragma("unroll") for (int n = 0; n < 2; ++n) _Pragma("unroll") for (int k = 0; k < 2; ++k) \
;         acc[ai][bj][m][n] = __builtin_amdgcn_mfma_f32_16x16x32_bf16(Bt[n][k], At[m][k], acc[ai][bj][m][n], 0, 0, 0); __builtin_amdgcn_s_setprio(0); } while (0)
; #define PG8_WAIT_V(n) asm volatile("s_waitcnt vmcnt(" #n ")" ::: "memory")
; #define PG8_WAIT_L(n) asm volatile("s_waitcnt lgkmcnt(" #n ")" ::: "memory")
; #define PG8_BAR __builtin_amdgcn_s_barrier()
; #define PG8_SCHED __builtin_amdgcn_sched_barrier(0)
; template <class Epi, class Sched, bool ALIGN_EPI = false, bool SP2 = false>
; __device__ __forceinline__ void gemm_phase(PG8_LAS unsigned char* lds, const Gemm g, const Sched& S, const Epi& E, int tid_in) {
;     ...
;             PG8_LDB(B0, 0, 0); PG8_LDB(B1, 0, 1); PG8_SCHED; PG8_LDA(At, 0, 0); PG8_STAGE(PG8_SA(1, 1), a1 + hstepA, voffA);
;             PG8_WAIT_V(8); PG8_WAIT_L(0); PG8_BAR; PG8_MMA(0, 0, At, B0); PG8_MMA(0, 1, At, B1); PG8_BAR; PG8_SCHED;
;             PG8_LDA(At, 0, 1); PG8_STAGE(PG8_SB(0, 0), b2, voffB); PG8_STAGE(PG8_SB(0, 1), b2 + hstepB, voffB); PG8_STAGE(PG8_SA(0, 0), a2, voffA);
;             PG8_WAIT_V(8); PG8_WAIT_L(0); PG8_BAR; PG8_MMA(1, 0, At, B0); PG8_MMA(1, 1, At, B1); PG8_BAR; PG8_SCHED;
.LBB0_1037:
	v_add_u32_e32 v0, 0x10000, v236
	ds_read_b128 v[132:135], v0
	ds_read_b128 v[136:139], v0 offset:1024
	ds_read_b128 v[140:143], v0 offset:2048
	ds_read_b128 v[144:147], v0 offset:3072
	v_add_u32_e32 v0, 0x14000, v236
	ds_read_b128 v[148:151], v0
	ds_read_b128 v[152:155], v0 offset:1024
	ds_read_b128 v[156:159], v0 offset:2048
	ds_read_b128 v[160:163], v0 offset:3072
	s_add_u32 s16, s12, 0x100
	s_addc_u32 s17, s13, 0
	s_sub_i32 s12, s12, s4
	s_add_i32 s12, s12, 0xc0080
	s_sub_i32 s39, s12, 0xc0000
	s_cmp_eq_u32 s38, 12
	s_cselect_b32 s13, s24, s16
	s_mov_b32 m0, s76
	ds_read_b128 v[164:167], v237
	ds_read_b128 v[168:171], v237 offset:1024
	ds_read_b128 v[172:175], v237 offset:2048
	ds_read_b128 v[176:179], v237 offset:3072
	ds_read_b128 v[180:183], v237 offset:4096
	ds_read_b128 v[184:187], v237 offset:5120
	ds_read_b128 v[188:191], v237 offset:6144
	ds_read_b128 v[192:195], v237 offset:7168
	s_mov_b32 m0, s73
	s_nop 0
	buffer_load_dwordx4 v222, s[4:7], s39 offen lds
	s_mov_b32 m0, s76
	s_nop 0
	buffer_load_dwordx4 v220, s[4:7], s12 offen lds
	s_mov_b32 m0, s77
	s_nop 0
	buffer_load_dwordx4 v222, s[4:7], s12 offen lds
	s_waitcnt vmcnt(8)
	s_waitcnt lgkmcnt(0)
	s_setprio 1
	s_barrier
	v_mfma_f32_16x16x32_bf16 v[128:131], v[132:135], v[164:167], v[128:131]
	v_mfma_f32_16x16x32_bf16 v[124:127], v[140:143], v[164:167], v[124:127]
	v_mfma_f32_16x16x32_bf16 v[116:119], v[140:143], v[172:175], v[116:119]
	v_mfma_f32_16x16x32_bf16 v[120:123], v[132:135], v[172:175], v[120:123]
	v_mfma_f32_16x16x32_bf16 v[112:115], v[132:135], v[180:183], v[112:115]
	v_mfma_f32_16x16x32_bf16 v[108:111], v[140:143], v[180:183], v[108:111]
	v_mfma_f32_16x16x32_bf16 v[100:103], v[140:143], v[188:191], v[100:103]
	v_mfma_f32_16x16x32_bf16 v[104:107], v[132:135], v[188:191], v[104:107]
	v_mfma_f32_16x16x32_bf16 v[128:131], v[136:139], v[168:171], v[128:131]
	v_mfma_f32_16x16x32_bf16 v[124:127], v[144:147], v[168:171], v[124:127]
	v_mfma_f32_16x16x32_bf16 v[116:119], v[144:147], v[176:179], v[116:119]
	v_mfma_f32_16x16x32_bf16 v[120:123], v[136:139], v[176:179], v[120:123]
	v_mfma_f32_16x16x32_bf16 v[112:115], v[136:139], v[184:187], v[112:115]
	v_mfma_f32_16x16x32_bf16 v[108:111], v[144:147], v[184:187], v[108:111]
	v_mfma_f32_16x16x32_bf16 v[100:103], v[144:147], v[192:195], v[100:103]
	v_mfma_f32_16x16x32_bf16 v[104:107], v[136:139], v[192:195], v[104:107]
	v_mfma_f32_16x16x32_bf16 v[96:99], v[148:151], v[164:167], v[96:99]
	v_mfma_f32_16x16x32_bf16 v[92:95], v[156:159], v[164:167], v[92:95]
	v_mfma_f32_16x16x32_bf16 v[84:87], v[156:159], v[172:175], v[84:87]
	v_mfma_f32_16x16x32_bf16 v[88:91], v[148:151], v[172:175], v[88:91]
	v_mfma_f32_16x16x32_bf16 v[80:83], v[148:151], v[180:183], v[80:83]
	v_mfma_f32_16x16x32_bf16 v[76:79], v[156:159], v[180:183], v[76:79]
	v_mfma_f32_16x16x32_bf16 v[68:71], v[156:159], v[188:191], v[68:71]
	v_mfma_f32_16x16x32_bf16 v[72:75], v[148:151], v[188:191], v[72:75]
	v_mfma_f32_16x16x32_bf16 v[96:99], v[152:155], v[168:171], v[96:99]
	v_mfma_f32_16x16x32_bf16 v[92:95], v[160:163], v[168:171], v[92:95]
	v_mfma_f32_16x16x32_bf16 v[84:87], v[160:163], v[176:179], v[84:87]
	v_mfma_f32_16x16x32_bf16 v[88:91], v[152:155], v[176:179], v[88:91]
	v_mfma_f32_16x16x32_bf16 v[80:83], v[152:155], v[184:187], v[80:83]
	v_mfma_f32_16x16x32_bf16 v[76:79], v[160:163], v[184:187], v[76:79]
	v_mfma_f32_16x16x32_bf16 v[68:71], v[160:163], v[192:195], v[68:71]
	v_mfma_f32_16x16x32_bf16 v[72:75], v[152:155], v[192:195], v[72:75]
	s_barrier
	s_setprio 0
	s_cselect_b32 s12, s18, s19
	s_mov_b32 m0, s26
	s_mov_b32 s46, s6
	s_mov_b32 s47, s7
	s_sub_i32 s12, s12, s44
	ds_read_b128 v[164:167], v237 offset:16384
	ds_read_b128 v[168:171], v237 offset:17408
	ds_read_b128 v[172:175], v237 offset:18432
	ds_read_b128 v[176:179], v237 offset:19456
	ds_read_b128 v[180:183], v237 offset:20480
	ds_read_b128 v[184:187], v237 offset:21504
	ds_read_b128 v[188:191], v237 offset:22528
	ds_read_b128 v[192:195], v237 offset:23552
	buffer_load_dwordx4 v221, s[44:47], s12 offen lds
	s_mov_b32 m0, s53
	s_add_i32 s39, s12, 0x40000
	buffer_load_dwordx4 v223, s[44:47], s12 offen lds
	s_mov_b32 m0, s60
	s_sub_i32 s13, s13, s4
	buffer_load_dwordx4 v221, s[44:47], s39 offen lds
	s_mov_b32 m0, s61
	s_nop 0
	buffer_load_dwordx4 v223, s[44:47], s39 offen lds
	s_mov_b32 m0, s21
	s_nop 0
	buffer_load_dwordx4 v220, s[4:7], s13 offen lds
	s_waitcnt vmcnt(7)
	s_waitcnt lgkmcnt(0)
	s_setprio 1
	s_barrier
	v_mfma_f32_16x16x32_bf16 v[64:67], v[132:135], v[164:167], v[64:67]
	v_mfma_f32_16x16x32_bf16 v[60:63], v[140:143], v[164:167], v[60:63]
	v_mfma_f32_16x16x32_bf16 v[52:55], v[140:143], v[172:175], v[52:55]
	v_mfma_f32_16x16x32_bf16 v[56:59], v[132:135], v[172:175], v[56:59]
	v_mfma_f32_16x16x32_bf16 v[48:51], v[132:135], v[180:183], v[48:51]
	v_mfma_f32_16x16x32_bf16 v[44:47], v[140:143], v[180:183], v[44:47]
	v_mfma_f32_16x16x32_bf16 v[36:39], v[140:143], v[188:191], v[36:39]
	v_mfma_f32_16x16x32_bf16 v[40:43], v[132:135], v[188:191], v[40:43]
	v_mfma_f32_16x16x32_bf16 v[64:67], v[136:139], v[168:171], v[64:67]
	v_mfma_f32_16x16x32_bf16 v[60:63], v[144:147], v[168:171], v[60:63]
	v_mfma_f32_16x16x32_bf16 v[52:55], v[144:147], v[176:179], v[52:55]
	v_mfma_f32_16x16x32_bf16 v[56:59], v[136:139], v[176:179], v[56:59]
	v_mfma_f32_16x16x32_bf16 v[48:51], v[136:139], v[184:187], v[48:51]
	v_mfma_f32_16x16x32_bf16 v[44:47], v[144:147], v[184:187], v[44:47]
	v_mfma_f32_16x16x32_bf16 v[36:39], v[144:147], v[192:195], v[36:39]
	v_mfma_f32_16x16x32_bf16 v[40:43], v[136:139], v[192:195], v[40:43]
	v_mfma_f32_16x16x32_bf16 v[32:35], v[148:151], v[164:167], v[32:35]
	v_mfma_f32_16x16x32_bf16 v[28:31], v[156:159], v[164:167], v[28:31]
	v_mfma_f32_16x16x32_bf16 v[20:23], v[156:159], v[172:175], v[20:23]
	v_mfma_f32_16x16x32_bf16 v[24:27], v[148:151], v[172:175], v[24:27]
	v_mfma_f32_16x16x32_bf16 v[16:19], v[148:151], v[180:183], v[16:19]
	v_mfma_f32_16x16x32_bf16 v[12:15], v[156:159], v[180:183], v[12:15]
	v_mfma_f32_16x16x32_bf16 v[2:5], v[156:159], v[188:191], v[4:7]
	v_mfma_f32_16x16x32_bf16 v[8:11], v[148:151], v[188:191], v[8:11]
	v_mfma_f32_16x16x32_bf16 v[32:35], v[152:155], v[168:171], v[32:35]
	v_mfma_f32_16x16x32_bf16 v[28:31], v[160:163], v[168:171], v[28:31]
	v_mfma_f32_16x16x32_bf16 v[20:23], v[160:163], v[176:179], v[20:23]
	v_mfma_f32_16x16x32_bf16 v[24:27], v[152:155], v[176:179], v[24:27]
	v_mfma_f32_16x16x32_bf16 v[16:19], v[152:155], v[184:187], v[16:19]
	v_mfma_f32_16x16x32_bf16 v[12:15], v[160:163], v[184:187], v[12:15]
	v_mfma_f32_16x16x32_bf16 v[2:5], v[160:163], v[192:195], v[2:5]
	v_mfma_f32_16x16x32_bf16 v[8:11], v[152:155], v[192:195], v[8:11]
	s_barrier
; #define PG8_STAGE(bufoff, gbase, voff) do { const int so_ = (int)(unsigned)((const char*)(gbase) - base_##voff); _Pragma("unroll") for (int _i = 0; _i < 2; ++_i) \
;         __builtin_amdgcn_raw_ptr_buffer_load_lds(rs_##voff, (PG8_LAS unsigned*)(lds + (bufoff) + ldsw + _i * 8192), 16, (int)(voff)[_i], so_, 0, 0); } while (0)
; #define PG8_LDA(dst, b, h) do { _Pragma("unroll") for (int m = 0; m < 4; ++m) _Pragma("unroll") for (int k = 0; k < 2; ++k) dst[m][k] = *(const PG8_LAS bf16x8*)(lds + PG8_SA(b, h) + aoff + m * 2048 + k * 1024); } while (0)
; #define PG8_LDB(dst, b, h) do { _Pragma("unroll") for (int n = 0; n < 2; ++n) _Pragma("unroll") for (int k = 0; k < 2; ++k) dst[n][k] = *(const PG8_LAS bf16x8*)(lds + PG8_SB(b, h) + boff + n * 2048 + k * 1024); } while (0)
; #define PG8_MMA(ai, bj, At, Bt) do { __builtin_amdgcn_s_setprio(1); _Pragma("unroll") for (int m = 0; m < 4; ++m) _Pragma("unroll") for (int n = 0; n < 2; ++n) _Pragma("unroll") for (int k = 0; k < 2; ++k) \
;         acc[ai][bj][m][n] = __builtin_amdgcn_mfma_f32_16x16x32_bf16(Bt[n][k], At[m][k], acc[ai][bj][m][n], 0, 0, 0); __builtin_amdgcn_s_setprio(0); } while (0)
; #define PG8_WAIT_V(n) asm volatile("s_waitcnt vmcnt(" #n ")" ::: "memory")
; #define PG8_WAIT_L(n) asm volatile("s_waitcnt lgkmcnt(" #n ")" ::: "memory")
; #define PG8_BAR __builtin_amdgcn_s_barrier()
; #define PG8_SCHED __builtin_amdgcn_sched_barrier(0)
; template <class Epi, class Sched, bool ALIGN_EPI = false, bool SP2 = false>
; __device__ __forceinline__ void gemm_phase(PG8_LAS unsigned char* lds, const Gemm g, const Sched& S, const Epi& E, int tid_in) {
;     ...
;             PG8_LDB(B0, 1, 0); PG8_LDB(B1, 1, 1); PG8_SCHED; PG8_LDA(At, 1, 0); PG8_STAGE(PG8_SA(0, 1), a2 + hstepA, voffA);
;             PG8_WAIT_V(8); PG8_WAIT_L(0); PG8_BAR; PG8_MMA(0, 0, At, B0); PG8_MMA(0, 1, At, B1); PG8_BAR; PG8_SCHED;
;             PG8_LDA(At, 1, 1); PG8_STAGE(PG8_SB(1, 0), b3, voffB); PG8_STAGE(PG8_SB(1, 1), b3 + hstepB, voffB); PG8_STAGE(PG8_SA(1, 0), a3, voffA);
;             PG8_WAIT_V(8); PG8_WAIT_L(0); PG8_BAR; PG8_MMA(1, 0, At, B0); PG8_MMA(1, 1, At, B1); PG8_BAR; PG8_SCHED;
	s_setprio 0
	v_add_u32_e32 v0, 0x18000, v236
	ds_read_b128 v[132:135], v0
	ds_read_b128 v[136:139], v0 offset:1024
	ds_read_b128 v[140:143], v0 offset:2048
	ds_read_b128 v[144:147], v0 offset:3072
	v_add_u32_e32 v0, 0x1c000, v236
	ds_read_b128 v[148:151], v0
	ds_read_b128 v[152:155], v0 offset:1024
	ds_read_b128 v[156:159], v0 offset:2048
	ds_read_b128 v[160:163], v0 offset:3072
	s_add_i32 s39, s13, 0xc0000
	s_mov_b32 m0, s63
	ds_read_b128 v[164:167], v237 offset:32768
	ds_read_b128 v[168:171], v237 offset:33792
	ds_read_b128 v[172:175], v237 offset:34816
	ds_read_b128 v[176:179], v237 offset:35840
	ds_read_b128 v[180:183], v237 offset:36864
	ds_read_b128 v[184:187], v237 offset:37888
	ds_read_b128 v[188:191], v237 offset:38912
	ds_read_b128 v[192:195], v237 offset:39936
	s_mov_b32 m0, s62
	s_nop 0
	buffer_load_dwordx4 v222, s[4:7], s13 offen lds
	s_mov_b32 m0, s63
	s_nop 0
	buffer_load_dwordx4 v220, s[4:7], s39 offen lds
	s_mov_b32 m0, s66
	s_nop 0
	buffer_load_dwordx4 v222, s[4:7], s39 offen lds
	s_waitcnt vmcnt(8)
	s_waitcnt lgkmcnt(0)
	s_setprio 1
	s_barrier
	v_mfma_f32_16x16x32_bf16 v[128:131], v[132:135], v[164:167], v[128:131]
	v_mfma_f32_16x16x32_bf16 v[124:127], v[140:143], v[164:167], v[124:127]
	v_mfma_f32_16x16x32_bf16 v[116:119], v[140:143], v[172:175], v[116:119]
	v_mfma_f32_16x16x32_bf16 v[120:123], v[132:135], v[172:175], v[120:123]
	v_mfma_f32_16x16x32_bf16 v[112:115], v[132:135], v[180:183], v[112:115]
	v_mfma_f32_16x16x32_bf16 v[108:111], v[140:143], v[180:183], v[108:111]
	v_mfma_f32_16x16x32_bf16 v[100:103], v[140:143], v[188:191], v[100:103]
	v_mfma_f32_16x16x32_bf16 v[104:107], v[132:135], v[188:191], v[104:107]
	v_mfma_f32_16x16x32_bf16 v[128:131], v[136:139], v[168:171], v[128:131]
	v_mfma_f32_16x16x32_bf16 v[124:127], v[144:147], v[168:171], v[124:127]
	v_mfma_f32_16x16x32_bf16 v[116:119], v[144:147], v[176:179], v[116:119]
	v_mfma_f32_16x16x32_bf16 v[120:123], v[136:139], v[176:179], v[120:123]
	v_mfma_f32_16x16x32_bf16 v[112:115], v[136:139], v[184:187], v[112:115]
	v_mfma_f32_16x16x32_bf16 v[108:111], v[144:147], v[184:187], v[108:111]
	v_mfma_f32_16x16x32_bf16 v[100:103], v[144:147], v[192:195], v[100:103]
	v_mfma_f32_16x16x32_bf16 v[104:107], v[136:139], v[192:195], v[104:107]
	v_mfma_f32_16x16x32_bf16 v[96:99], v[148:151], v[164:167], v[96:99]
	v_mfma_f32_16x16x32_bf16 v[92:95], v[156:159], v[164:167], v[92:95]
	v_mfma_f32_16x16x32_bf16 v[84:87], v[156:159], v[172:175], v[84:87]
	v_mfma_f32_16x16x32_bf16 v[88:91], v[148:151], v[172:175], v[88:91]
	v_mfma_f32_16x16x32_bf16 v[80:83], v[148:151], v[180:183], v[80:83]
	v_mfma_f32_16x16x32_bf16 v[76:79], v[156:159], v[180:183], v[76:79]
	v_mfma_f32_16x16x32_bf16 v[68:71], v[156:159], v[188:191], v[68:71]
	v_mfma_f32_16x16x32_bf16 v[72:75], v[148:151], v[188:191], v[72:75]
	v_mfma_f32_16x16x32_bf16 v[96:99], v[152:155], v[168:171], v[96:99]
	v_mfma_f32_16x16x32_bf16 v[92:95], v[160:163], v[168:171], v[92:95]
	v_mfma_f32_16x16x32_bf16 v[84:87], v[160:163], v[176:179], v[84:87]
	v_mfma_f32_16x16x32_bf16 v[88:91], v[152:155], v[176:179], v[88:91]
	v_mfma_f32_16x16x32_bf16 v[80:83], v[152:155], v[184:187], v[80:83]
	v_mfma_f32_16x16x32_bf16 v[76:79], v[160:163], v[184:187], v[76:79]
	v_mfma_f32_16x16x32_bf16 v[68:71], v[160:163], v[192:195], v[68:71]
	v_mfma_f32_16x16x32_bf16 v[72:75], v[152:155], v[192:195], v[72:75]
	s_barrier
	s_setprio 0
	s_mov_b32 m0, s69
	s_add_i32 s39, s12, 0x80
	ds_read_b128 v[164:167], v237 offset:49152
	ds_read_b128 v[168:171], v237 offset:50176
	ds_read_b128 v[172:175], v237 offset:51200
	ds_read_b128 v[176:179], v237 offset:52224
	ds_read_b128 v[180:183], v237 offset:53248
	ds_read_b128 v[184:187], v237 offset:54272
	ds_read_b128 v[188:191], v237 offset:55296
	ds_read_b128 v[192:195], v237 offset:56320
	buffer_load_dwordx4 v221, s[44:47], s39 offen lds
	s_mov_b32 m0, s71
	s_add_i32 s12, s12, 0x40080
	buffer_load_dwordx4 v223, s[44:47], s39 offen lds
	s_mov_b32 m0, s74
	s_addk_i32 s13, 0x80
	buffer_load_dwordx4 v221, s[44:47], s12 offen lds
	s_mov_b32 m0, s75
	s_nop 0
	buffer_load_dwordx4 v223, s[44:47], s12 offen lds
	s_mov_b32 m0, s72
	s_nop 0
	buffer_load_dwordx4 v220, s[4:7], s13 offen lds
	s_waitcnt vmcnt(7)
	s_waitcnt lgkmcnt(0)
	s_setprio 1
	s_barrier
	v_mfma_f32_16x16x32_bf16 v[64:67], v[132:135], v[164:167], v[64:67]
	v_mfma_f32_16x16x32_bf16 v[60:63], v[140:143], v[164:167], v[60:63]
	v_mfma_f32_16x16x32_bf16 v[52:55], v[140:143], v[172:175], v[52:55]
	v_mfma_f32_16x16x32_bf16 v[56:59], v[132:135], v[172:175], v[56:59]
	v_mfma_f32_16x16x32_bf16 v[48:51], v[132:135], v[180:183], v[48:51]
	v_mfma_f32_16x16x32_bf16 v[44:47], v[140:143], v[180:183], v[44:47]
	v_mfma_f32_16x16x32_bf16 v[36:39], v[140:143], v[188:191], v[36:39]
	v_mfma_f32_16x16x32_bf16 v[40:43], v[132:135], v[188:191], v[40:43]
	v_mfma_f32_16x16x32_bf16 v[64:67], v[136:139], v[168:171], v[64:67]
	v_mfma_f32_16x16x32_bf16 v[60:63], v[144:147], v[168:171], v[60:63]
	v_mfma_f32_16x16x32_bf16 v[52:55], v[144:147], v[176:179], v[52:55]
	v_mfma_f32_16x16x32_bf16 v[56:59], v[136:139], v[176:179], v[56:59]
	v_mfma_f32_16x16x32_bf16 v[48:51], v[136:139], v[184:187], v[48:51]
	v_mfma_f32_16x16x32_bf16 v[44:47], v[144:147], v[184:187], v[44:47]
	v_mfma_f32_16x16x32_bf16 v[36:39], v[144:147], v[192:195], v[36:39]
	v_mfma_f32_16x16x32_bf16 v[40:43], v[136:139], v[192:195], v[40:43]
	v_mfma_f32_16x16x32_bf16 v[32:35], v[148:151], v[164:167], v[32:35]
	v_mfma_f32_16x16x32_bf16 v[28:31], v[156:159], v[164:167], v[28:31]
	v_mfma_f32_16x16x32_bf16 v[20:23], v[156:159], v[172:175], v[20:23]
	v_mfma_f32_16x16x32_bf16 v[24:27], v[148:151], v[172:175], v[24:27]
	v_mfma_f32_16x16x32_bf16 v[16:19], v[148:151], v[180:183], v[16:19]
	v_mfma_f32_16x16x32_bf16 v[12:15], v[156:159], v[180:183], v[12:15]
	v_mfma_f32_16x16x32_bf16 v[2:5], v[156:159], v[188:191], v[2:5]
	v_mfma_f32_16x16x32_bf16 v[6:9], v[148:151], v[188:191], v[8:11]
	v_mfma_f32_16x16x32_bf16 v[32:35], v[152:155], v[168:171], v[32:35]
	v_mfma_f32_16x16x32_bf16 v[28:31], v[160:163], v[168:171], v[28:31]
	v_mfma_f32_16x16x32_bf16 v[20:23], v[160:163], v[176:179], v[20:23]
	v_mfma_f32_16x16x32_bf16 v[24:27], v[152:155], v[176:179], v[24:27]
	v_mfma_f32_16x16x32_bf16 v[16:19], v[152:155], v[184:187], v[16:19]
	v_mfma_f32_16x16x32_bf16 v[12:15], v[160:163], v[184:187], v[12:15]
	v_mfma_f32_16x16x32_bf16 v[8:11], v[152:155], v[192:195], v[6:9]
	v_mfma_f32_16x16x32_bf16 v[4:7], v[160:163], v[192:195], v[2:5]
	s_barrier
	s_setprio 0
	s_add_i32 s38, s38, 2
	s_add_u32 s19, s19, 0x100
	s_addc_u32 s23, s23, 0
	s_cmp_gt_u32 s38, 13
	s_mov_b64 s[12:13], s[16:17]
	s_cbranch_scc0 .LBB0_1037
	s_and_b64 vcc, exec, s[14:15]
	s_cbranch_vccz .LBB0_1040
	s_barrier
